# scan consumer: state decay with packed f32 multiplies (8 instead of 16 VALU per chunk)
# baseline (speedup 1.0000x reference)
; __device__ __forceinline__ void p3_rwkv_state(Frame& F, const Args& a) {
;     ...
;         for (int n = 0; n < NC; n += 2) { SP_STEP(C, N, n); SP_STEP(N, C, n + 1); }
.Lscan_loop:
	v_add_u32_e32 v80, s10, v77
	v_add_u32_e32 v81, s10, v78
	v_add_u32_e32 v82, s10, v79
	s_add_i32 s10, s10, 0x2800
	s_cmp_eq_u32 s10, 0x25800
	s_cselect_b32 s10, 0, s10
	v_mfma_f32_16x16x32_bf16 v[24:27], v[32:35], v[16:19], v[24:27]
	v_mfma_f32_16x16x32_bf16 v[28:31], v[40:43], v[16:19], v[28:31]
	v_mfma_f32_16x16x32_bf16 v[24:27], v[36:39], v[20:23], v[24:27]
	v_mfma_f32_16x16x32_bf16 v[28:31], v[44:47], v[20:23], v[28:31]
	ds_read_b128 v[32:35], v80
	ds_read_b128 v[36:39], v80 offset:1024
	ds_read_b128 v[40:43], v80 offset:2048
	ds_read_b128 v[44:47], v80 offset:3072
	ds_read2st64_b64 v[96:99], v81 offset0:16 offset1:17
	s_waitcnt lgkmcnt(10)
	v_pk_mul_f32 v[0:1], v[64:65], v[0:1]
	v_pk_mul_f32 v[2:3], v[66:67], v[2:3]
	v_pk_mul_f32 v[4:5], v[68:69], v[4:5]
	v_pk_mul_f32 v[6:7], v[70:71], v[6:7]
	v_pk_mul_f32 v[8:9], v[72:73], v[8:9]
	v_pk_mul_f32 v[10:11], v[74:75], v[10:11]
	v_pk_mul_f32 v[12:13], v[88:89], v[12:13]
	v_pk_mul_f32 v[14:15], v[90:91], v[14:15]
	ds_read_b128 v[64:67], v82 offset:9728
	ds_read_b128 v[68:71], v82 offset:9744
	ds_read_b128 v[72:75], v82 offset:9760
	ds_read_b128 v[88:91], v82 offset:9776
	v_cvt_pk_bf16_f32 v94, v24, v25
	v_cvt_pk_bf16_f32 v95, v26, v27
	s_waitcnt lgkmcnt(9)
	s_nop 1
	v_mfma_f32_16x16x32_bf16 v[0:3], v[48:51], v[92:95], v[0:3]
	v_mfma_f32_16x16x32_bf16 v[4:7], v[52:55], v[92:95], v[4:7]
	v_mfma_f32_16x16x32_bf16 v[8:11], v[56:59], v[92:95], v[8:11]
	v_mfma_f32_16x16x32_bf16 v[12:15], v[60:63], v[92:95], v[12:15]
	v_cvt_pk_bf16_f32 v84, v28, v29
	v_cvt_pk_bf16_f32 v85, v30, v31
	ds_read2st64_b64 v[48:51], v81 offset0:12 offset1:8
	ds_read2st64_b64 v[52:55], v81 offset0:13 offset1:9
	ds_read2st64_b64 v[56:59], v81 offset0:14 offset1:10
	ds_read2st64_b64 v[60:63], v81 offset0:15 offset1:11
	ds_read_b64 v[92:93], v81 offset:9216
	global_store_short v83, v84, s[8:9] offset:-4096
	global_store_short_d16_hi v83, v84, s[8:9] offset:-2048
	global_store_short v83, v85, s[8:9]
	global_store_short_d16_hi v83, v85, s[8:9] offset:2048
	s_add_u32 s8, s8, 0x8000
	s_addc_u32 s9, s9, 0
	s_waitcnt lgkmcnt(9)
	v_lshlrev_b32_e32 v24, 16, v96
	v_and_b32_e32 v25, 0xffff0000, v96
	v_lshlrev_b32_e32 v26, 16, v97
	v_and_b32_e32 v27, 0xffff0000, v97
	v_lshlrev_b32_e32 v28, 16, v98
	v_and_b32_e32 v29, 0xffff0000, v98
	v_lshlrev_b32_e32 v30, 16, v99
	v_and_b32_e32 v31, 0xffff0000, v99
	v_cvt_pk_bf16_f32 v16, v0, v1
	v_cvt_pk_bf16_f32 v17, v2, v3
	v_cvt_pk_bf16_f32 v18, v4, v5
	v_cvt_pk_bf16_f32 v19, v6, v7
	v_cvt_pk_bf16_f32 v20, v8, v9
	v_cvt_pk_bf16_f32 v21, v10, v11
	v_cvt_pk_bf16_f32 v22, v12, v13
	v_cvt_pk_bf16_f32 v23, v14, v15
	v_add_u32_e32 v80, s10, v77
	v_add_u32_e32 v81, s10, v78
	v_add_u32_e32 v82, s10, v79
	s_add_i32 s10, s10, 0x2800
	s_cmp_eq_u32 s10, 0x25800
	s_cselect_b32 s10, 0, s10
	v_mfma_f32_16x16x32_bf16 v[24:27], v[32:35], v[16:19], v[24:27]
	v_mfma_f32_16x16x32_bf16 v[28:31], v[40:43], v[16:19], v[28:31]
	v_mfma_f32_16x16x32_bf16 v[24:27], v[36:39], v[20:23], v[24:27]
	v_mfma_f32_16x16x32_bf16 v[28:31], v[44:47], v[20:23], v[28:31]
	ds_read_b128 v[32:35], v80
	ds_read_b128 v[36:39], v80 offset:1024
	ds_read_b128 v[40:43], v80 offset:2048
	ds_read_b128 v[44:47], v80 offset:3072
	ds_read2st64_b64 v[96:99], v81 offset0:16 offset1:17
	s_waitcnt lgkmcnt(10)
	v_pk_mul_f32 v[0:1], v[64:65], v[0:1]
	v_pk_mul_f32 v[2:3], v[66:67], v[2:3]
	v_pk_mul_f32 v[4:5], v[68:69], v[4:5]
	v_pk_mul_f32 v[6:7], v[70:71], v[6:7]
	v_pk_mul_f32 v[8:9], v[72:73], v[8:9]
	v_pk_mul_f32 v[10:11], v[74:75], v[10:11]
	v_pk_mul_f32 v[12:13], v[88:89], v[12:13]
	v_pk_mul_f32 v[14:15], v[90:91], v[14:15]
	ds_read_b128 v[64:67], v82 offset:9728
	ds_read_b128 v[68:71], v82 offset:9744
	ds_read_b128 v[72:75], v82 offset:9760
	ds_read_b128 v[88:91], v82 offset:9776
	v_cvt_pk_bf16_f32 v94, v24, v25
	v_cvt_pk_bf16_f32 v95, v26, v27
	s_waitcnt lgkmcnt(9)
	s_nop 1
	v_mfma_f32_16x16x32_bf16 v[0:3], v[48:51], v[92:95], v[0:3]
	v_mfma_f32_16x16x32_bf16 v[4:7], v[52:55], v[92:95], v[4:7]
	v_mfma_f32_16x16x32_bf16 v[8:11], v[56:59], v[92:95], v[8:11]
	v_mfma_f32_16x16x32_bf16 v[12:15], v[60:63], v[92:95], v[12:15]
	v_cvt_pk_bf16_f32 v84, v28, v29
	v_cvt_pk_bf16_f32 v85, v30, v31
	ds_read2st64_b64 v[48:51], v81 offset0:12 offset1:8
	ds_read2st64_b64 v[52:55], v81 offset0:13 offset1:9
	ds_read2st64_b64 v[56:59], v81 offset0:14 offset1:10
	ds_read2st64_b64 v[60:63], v81 offset0:15 offset1:11
	ds_read_b64 v[92:93], v81 offset:9216
	global_store_short v83, v84, s[8:9] offset:-4096
	global_store_short_d16_hi v83, v84, s[8:9] offset:-2048
	global_store_short v83, v85, s[8:9]
	global_store_short_d16_hi v83, v85, s[8:9] offset:2048
	s_add_u32 s8, s8, 0x8000
	s_addc_u32 s9, s9, 0
	s_waitcnt lgkmcnt(9)
	v_lshlrev_b32_e32 v24, 16, v96
	v_and_b32_e32 v25, 0xffff0000, v96
	v_lshlrev_b32_e32 v26, 16, v97
	v_and_b32_e32 v27, 0xffff0000, v97
	v_lshlrev_b32_e32 v28, 16, v98
	v_and_b32_e32 v29, 0xffff0000, v98
	v_lshlrev_b32_e32 v30, 16, v99
	v_and_b32_e32 v31, 0xffff0000, v99
	v_cvt_pk_bf16_f32 v16, v0, v1
	v_cvt_pk_bf16_f32 v17, v2, v3
	v_cvt_pk_bf16_f32 v18, v4, v5
	v_cvt_pk_bf16_f32 v19, v6, v7
	v_cvt_pk_bf16_f32 v20, v8, v9
	v_cvt_pk_bf16_f32 v21, v10, v11
	v_cvt_pk_bf16_f32 v22, v12, v13
	v_cvt_pk_bf16_f32 v23, v14, v15
	s_barrier
	s_add_i32 s11, s11, 2
	s_cmpk_lt_u32 s11, 0x400
	s_cbranch_scc1 .Lscan_loop
	s_branch .LBB0_456
